# 8x4 loops: staging DMAs issued before the K-tile's first fragment reads (no ds_read in flight while pieces issue)
# speedup vs baseline: 1.0087x; 1.0087x over previous
; #define LDB_(dst, ks) _Pragma("unroll") for (int n = 0; n < 4; ++n) dst[n] = *(const bf16x8*)(sB + b_off + n * 2048 + (ks) * 1024)
; #define LDA_(dst, ks, h) _Pragma("unroll") for (int m = 0; m < 4; ++m) dst[m] = *(const bf16x8*)(sA + a_off + ((h) * 4 + m) * 2048 + (ks) * 1024)
; #define MMA_(A, B, h) _Pragma("unroll") for (int m = 0; m < 4; ++m) _Pragma("unroll") for (int n = 0; n < 4; ++n) \
;       acc[(h) * 4 + m][n] = SWAP ? MFMA16(B[n], A[m], acc[(h) * 4 + m][n]) : MFMA16(A[m], B[n], acc[(h) * 4 + m][n])
; template <int MF, int NF, bool SWAP = true>
; DI void gemm_main(f32x4 (&acc)[MF][NF], const u16* __restrict__ Ab, int lda, const u16* __restrict__ Bb, int ldb,
;                   int K, char* shm) {
;     ...
;   for (int t = 0; t < nt; ++t) {
;     const int cur = RING3 ? cur3 : (t & 1);
;     if constexpr (RING3) {
;       if (t + 2 < nt) G_STAGE(nxt3, t + 2);
;     } else {
;       if (t + 1 < nt) G_STAGE(cur ^ 1, t + 1);
;     }
;     const char* sA = shm + cur * STAGE;
;     const char* sB = sA + TILE_A;
;     if constexpr (MF == 8 && NF == 4) {
;       bf16x8 B0[4], B1[4], A0[4], A1[4], A2[4], A3[4];
;     ...
;       LDB_(B0, 0); LDA_(A0, 0, 0);
;       LDA_(A1, 0, 1); MMA_(A0, B0, 0);
;       LDB_(B1, 1); LDA_(A2, 1, 0); MMA_(A1, B0, 1);
;       LDA_(A3, 1, 1); MMA_(A2, B1, 0);
;       MMA_(A3, B1, 1);
.LBB0_146:
	s_and_b32 s19, s17, 0x10000
	s_cmp_gt_u32 s13, 14
	s_cbranch_scc1 .Lg_rot146_last
	s_cmp_eq_u32 s13, 0
	s_cbranch_scc1 .Lg_rot146_first
	v_mfma_f32_16x16x32_bf16 v[60:63], v[186:189], v[190:193], v[60:63]
	s_xor_b32 s20, s19, 0x10000
	v_add_u32_e32 v179, s20, v128
	v_mfma_f32_16x16x32_bf16 v[56:59], v[194:197], v[190:193], v[56:59]
	s_nop 0
	v_readfirstlane_b32 s20, v179
	s_nop 1
	s_add_u32 m0, s20, 0x0
	v_mfma_f32_16x16x32_bf16 v[52:55], v[198:201], v[190:193], v[52:55]
	global_load_lds_dwordx4 v251, s[98:99]
	s_add_u32 m0, s20, 0x2000
	v_mfma_f32_16x16x32_bf16 v[48:51], v[212:215], v[190:193], v[48:51]
	global_load_lds_dwordx4 v250, s[98:99]
	s_add_u32 m0, s20, 0x4000
	v_mfma_f32_16x16x32_bf16 v[44:47], v[186:189], v[216:219], v[44:47]
	global_load_lds_dwordx4 v249, s[98:99]
	s_add_u32 m0, s20, 0x6000
	v_mfma_f32_16x16x32_bf16 v[40:43], v[194:197], v[216:219], v[40:43]
	global_load_lds_dwordx4 v248, s[98:99]
	s_add_u32 m0, s20, 0x8000
	v_mfma_f32_16x16x32_bf16 v[36:39], v[198:201], v[216:219], v[36:39]
	global_load_lds_dwordx4 v247, s[100:101]
	s_add_u32 m0, s20, 0xa000
	v_mfma_f32_16x16x32_bf16 v[32:35], v[212:215], v[216:219], v[32:35]
	global_load_lds_dwordx4 v246, s[100:101]
	s_add_u32 m0, s20, 0xc000
	v_mfma_f32_16x16x32_bf16 v[28:31], v[186:189], v[220:223], v[28:31]
	global_load_lds_dwordx4 v245, s[100:101]
	s_add_u32 m0, s20, 0xe000
	v_mfma_f32_16x16x32_bf16 v[24:27], v[194:197], v[220:223], v[24:27]
	global_load_lds_dwordx4 v244, s[100:101]
	v_mfma_f32_16x16x32_bf16 v[20:23], v[198:201], v[220:223], v[20:23]
	s_add_u32 s98, s98, 0x80
	s_addc_u32 s99, s99, 0
	s_add_u32 s100, s100, 0x80
	s_addc_u32 s101, s101, 0
	v_add_u32_e32 v137, s19, v132
	v_add_u32_e32 v178, v137, v131
	ds_read_b128 v[138:141], v178 offset:32768
	ds_read_b128 v[142:145], v178 offset:34816
	ds_read_b128 v[146:149], v178 offset:36864
	ds_read_b128 v[150:153], v178 offset:38912
	v_add_u32_e32 v137, v137, v129
	ds_read_b128 v[154:157], v137
	ds_read_b128 v[158:161], v137 offset:2048
	ds_read_b128 v[162:165], v137 offset:4096
	ds_read_b128 v[166:169], v137 offset:6144
	ds_read_b128 v[170:173], v137 offset:8192
	v_mfma_f32_16x16x32_bf16 v[16:19], v[212:215], v[220:223], v[16:19]
	v_mfma_f32_16x16x32_bf16 v[12:15], v[186:189], v[224:227], v[12:15]
	v_mfma_f32_16x16x32_bf16 v[8:11], v[194:197], v[224:227], v[8:11]
	v_mfma_f32_16x16x32_bf16 v[4:7], v[198:201], v[224:227], v[4:7]
	v_mfma_f32_16x16x32_bf16 v[0:3], v[212:215], v[224:227], v[0:3]
	s_branch .Lg_rot146_main
.Lg_rot146_first:
	v_add_u32_e32 v174, s11, v136
	s_xor_b32 s20, s19, 0x10000
	v_add_u32_e32 v176, 64, v174
	v_add_u32_e32 v179, s20, v128
	v_ashrrev_i32_e32 v177, 31, v176
	v_lshlrev_b64 v[176:177], 1, v[176:177]
	v_readfirstlane_b32 s20, v179
	v_lshl_add_u64 v[180:181], s[0:1], 0, v[176:177]
	s_mov_b32 m0, s20
	v_add_u32_e32 v182, 0x2000, v179
	global_load_lds_dwordx4 v[180:181], off
	v_subrev_u32_e32 v251, s0, v180
	v_add_u32_e32 v180, 0x10040, v174
	v_ashrrev_i32_e32 v181, 31, v180
	v_lshlrev_b64 v[180:181], 1, v[180:181]
	v_readfirstlane_b32 s20, v182
	v_lshl_add_u64 v[184:185], s[0:1], 0, v[180:181]
	s_mov_b32 m0, s20
	v_add_u32_e32 v175, 0x4000, v179
	global_load_lds_dwordx4 v[184:185], off
	v_subrev_u32_e32 v250, s0, v184
	v_add_u32_e32 v184, 0x20040, v174
	v_ashrrev_i32_e32 v185, 31, v184
	v_lshlrev_b64 v[184:185], 1, v[184:185]
	v_readfirstlane_b32 s20, v175
	v_lshl_add_u64 v[182:183], s[0:1], 0, v[184:185]
	s_mov_b32 m0, s20
	v_add_u32_e32 v211, 0x6000, v179
	global_load_lds_dwordx4 v[182:183], off
	v_subrev_u32_e32 v249, s0, v182
	v_add_u32_e32 v182, 0x30040, v174
	v_ashrrev_i32_e32 v183, 31, v182
	v_lshlrev_b64 v[182:183], 1, v[182:183]
	v_readfirstlane_b32 s20, v211
	v_lshl_add_u64 v[174:175], s[0:1], 0, v[182:183]
	s_mov_b32 m0, s20
	v_lshl_add_u64 v[176:177], s[4:5], 0, v[176:177]
	global_load_lds_dwordx4 v[174:175], off
	v_subrev_u32_e32 v248, s0, v174
	v_add_u32_e32 v174, 0x8000, v179
	s_nop 0
	v_readfirstlane_b32 s20, v174
	s_mov_b32 m0, s20
	s_nop 0
	global_load_lds_dwordx4 v[176:177], off
	v_subrev_u32_e32 v247, s4, v176
	v_lshl_add_u64 v[176:177], s[4:5], 0, v[180:181]
	v_add_u32_e32 v180, 0xa000, v179
	s_nop 0
	v_readfirstlane_b32 s20, v180
	v_add_u32_e32 v180, 0xc000, v179
	s_mov_b32 m0, s20
	v_readfirstlane_b32 s20, v180
	v_add_u32_e32 v179, 0xe000, v179
	global_load_lds_dwordx4 v[176:177], off
	v_subrev_u32_e32 v246, s4, v176
	v_lshl_add_u64 v[176:177], s[4:5], 0, v[184:185]
	s_mov_b32 m0, s20
	v_readfirstlane_b32 s20, v179
	global_load_lds_dwordx4 v[176:177], off
	v_subrev_u32_e32 v245, s4, v176
	v_lshl_add_u64 v[176:177], s[4:5], 0, v[182:183]
	s_mov_b32 m0, s20
	s_nop 0
	global_load_lds_dwordx4 v[176:177], off
	v_subrev_u32_e32 v244, s4, v176
	s_add_u32 s98, s0, 0x80
	s_addc_u32 s99, s1, 0
	s_add_u32 s100, s4, 0x80
	s_addc_u32 s101, s5, 0
	v_add_u32_e32 v137, s19, v132
	v_add_u32_e32 v178, v137, v131
	ds_read_b128 v[138:141], v178 offset:32768
	ds_read_b128 v[142:145], v178 offset:34816
	ds_read_b128 v[146:149], v178 offset:36864
	ds_read_b128 v[150:153], v178 offset:38912
	v_add_u32_e32 v137, v137, v129
	ds_read_b128 v[154:157], v137
	ds_read_b128 v[158:161], v137 offset:2048
	ds_read_b128 v[162:165], v137 offset:4096
	ds_read_b128 v[166:169], v137 offset:6144
	ds_read_b128 v[170:173], v137 offset:8192
	s_branch .Lg_rot146_main
.Lg_rot146_last:
	v_add_u32_e32 v137, s19, v132
	v_add_u32_e32 v178, v137, v131
	ds_read_b128 v[138:141], v178 offset:32768
	ds_read_b128 v[142:145], v178 offset:34816
	ds_read_b128 v[146:149], v178 offset:36864
	ds_read_b128 v[150:153], v178 offset:38912
	v_add_u32_e32 v137, v137, v129
	ds_read_b128 v[154:157], v137
	ds_read_b128 v[158:161], v137 offset:2048
	ds_read_b128 v[162:165], v137 offset:4096
	ds_read_b128 v[166:169], v137 offset:6144
	ds_read_b128 v[170:173], v137 offset:8192
	v_mfma_f32_16x16x32_bf16 v[60:63], v[186:189], v[190:193], v[60:63]
	v_mfma_f32_16x16x32_bf16 v[56:59], v[194:197], v[190:193], v[56:59]
	v_mfma_f32_16x16x32_bf16 v[52:55], v[198:201], v[190:193], v[52:55]
	v_mfma_f32_16x16x32_bf16 v[48:51], v[212:215], v[190:193], v[48:51]
	v_mfma_f32_16x16x32_bf16 v[44:47], v[186:189], v[216:219], v[44:47]
	v_mfma_f32_16x16x32_bf16 v[40:43], v[194:197], v[216:219], v[40:43]
	v_mfma_f32_16x16x32_bf16 v[36:39], v[198:201], v[216:219], v[36:39]
	v_mfma_f32_16x16x32_bf16 v[32:35], v[212:215], v[216:219], v[32:35]
	v_mfma_f32_16x16x32_bf16 v[28:31], v[186:189], v[220:223], v[28:31]
	v_mfma_f32_16x16x32_bf16 v[24:27], v[194:197], v[220:223], v[24:27]
	v_mfma_f32_16x16x32_bf16 v[20:23], v[198:201], v[220:223], v[20:23]
	v_mfma_f32_16x16x32_bf16 v[16:19], v[212:215], v[220:223], v[16:19]
	v_mfma_f32_16x16x32_bf16 v[12:15], v[186:189], v[224:227], v[12:15]
	v_mfma_f32_16x16x32_bf16 v[8:11], v[194:197], v[224:227], v[8:11]
	v_mfma_f32_16x16x32_bf16 v[4:7], v[198:201], v[224:227], v[4:7]
	v_mfma_f32_16x16x32_bf16 v[0:3], v[212:215], v[224:227], v[0:3]

; #define LDB_(dst, ks) _Pragma("unroll") for (int n = 0; n < 4; ++n) dst[n] = *(const bf16x8*)(sB + b_off + n * 2048 + (ks) * 1024)
; #define LDA_(dst, ks, h) _Pragma("unroll") for (int m = 0; m < 4; ++m) dst[m] = *(const bf16x8*)(sA + a_off + ((h) * 4 + m) * 2048 + (ks) * 1024)
; #define MMA_(A, B, h) _Pragma("unroll") for (int m = 0; m < 4; ++m) _Pragma("unroll") for (int n = 0; n < 4; ++n) \
;       acc[(h) * 4 + m][n] = SWAP ? MFMA16(B[n], A[m], acc[(h) * 4 + m][n]) : MFMA16(A[m], B[n], acc[(h) * 4 + m][n])
; template <int MF, int NF, bool SWAP = true>
; DI void gemm_main(f32x4 (&acc)[MF][NF], const u16* __restrict__ Ab, int lda, const u16* __restrict__ Bb, int ldb,
;                   int K, char* shm) {
;     ...
;   for (int t = 0; t < nt; ++t) {
;     const int cur = RING3 ? cur3 : (t & 1);
;     if constexpr (RING3) {
;       if (t + 2 < nt) G_STAGE(nxt3, t + 2);
;     } else {
;       if (t + 1 < nt) G_STAGE(cur ^ 1, t + 1);
;     }
;     const char* sA = shm + cur * STAGE;
;     const char* sB = sA + TILE_A;
;     if constexpr (MF == 8 && NF == 4) {
;       bf16x8 B0[4], B1[4], A0[4], A1[4], A2[4], A3[4];
;     ...
;       LDB_(B0, 0); LDA_(A0, 0, 0);
;       LDA_(A1, 0, 1); MMA_(A0, B0, 0);
;       LDB_(B1, 1); LDA_(A2, 1, 0); MMA_(A1, B0, 1);
;       LDA_(A3, 1, 1); MMA_(A2, B1, 0);
;       MMA_(A3, B1, 1);
.LBB0_244:
	s_and_b32 s18, s15, 0x10000
	s_cmp_gt_u32 s17, 14
	s_cbranch_scc1 .Lg_rot244_last
	s_cmp_eq_u32 s17, 0
	s_cbranch_scc1 .Lg_rot244_first
	v_mfma_f32_16x16x32_bf16 v[60:63], v[188:191], v[192:195], v[60:63]
	s_xor_b32 s19, s18, 0x10000
	v_add_u32_e32 v179, s19, v128
	v_mfma_f32_16x16x32_bf16 v[56:59], v[196:199], v[192:195], v[56:59]
	s_nop 0
	v_readfirstlane_b32 s19, v179
	s_nop 1
	s_add_u32 m0, s19, 0x0
	v_mfma_f32_16x16x32_bf16 v[52:55], v[212:215], v[192:195], v[52:55]
	global_load_lds_dwordx4 v251, s[98:99]
	s_add_u32 m0, s19, 0x2000
	v_mfma_f32_16x16x32_bf16 v[48:51], v[216:219], v[192:195], v[48:51]
	global_load_lds_dwordx4 v250, s[98:99]
	s_add_u32 m0, s19, 0x4000
	v_mfma_f32_16x16x32_bf16 v[44:47], v[188:191], v[220:223], v[44:47]
	global_load_lds_dwordx4 v249, s[98:99]
	s_add_u32 m0, s19, 0x6000
	v_mfma_f32_16x16x32_bf16 v[40:43], v[196:199], v[220:223], v[40:43]
	global_load_lds_dwordx4 v248, s[98:99]
	s_add_u32 m0, s19, 0x8000
	v_mfma_f32_16x16x32_bf16 v[36:39], v[212:215], v[220:223], v[36:39]
	global_load_lds_dwordx4 v247, s[100:101]
	s_add_u32 m0, s19, 0xa000
	v_mfma_f32_16x16x32_bf16 v[32:35], v[216:219], v[220:223], v[32:35]
	global_load_lds_dwordx4 v246, s[100:101]
	s_add_u32 m0, s19, 0xc000
	v_mfma_f32_16x16x32_bf16 v[28:31], v[188:191], v[224:227], v[28:31]
	global_load_lds_dwordx4 v245, s[100:101]
	s_add_u32 m0, s19, 0xe000
	v_mfma_f32_16x16x32_bf16 v[24:27], v[196:199], v[224:227], v[24:27]
	global_load_lds_dwordx4 v244, s[100:101]
	v_mfma_f32_16x16x32_bf16 v[20:23], v[212:215], v[224:227], v[20:23]
	s_add_u32 s98, s98, 0x80
	s_addc_u32 s99, s99, 0
	s_add_u32 s100, s100, 0x80
	s_addc_u32 s101, s101, 0
	v_add_u32_e32 v154, s18, v136
	v_add_u32_e32 v178, v154, v132
	ds_read_b128 v[138:141], v178 offset:32768
	ds_read_b128 v[142:145], v178 offset:34816
	ds_read_b128 v[146:149], v178 offset:36864
	ds_read_b128 v[150:153], v178 offset:38912
	v_add_u32_e32 v186, v154, v129
	ds_read_b128 v[154:157], v186
	ds_read_b128 v[158:161], v186 offset:2048
	ds_read_b128 v[162:165], v186 offset:4096
	ds_read_b128 v[166:169], v186 offset:6144
	ds_read_b128 v[170:173], v186 offset:8192
	v_mfma_f32_16x16x32_bf16 v[16:19], v[216:219], v[224:227], v[16:19]
	v_mfma_f32_16x16x32_bf16 v[12:15], v[188:191], v[228:231], v[12:15]
	v_mfma_f32_16x16x32_bf16 v[8:11], v[196:199], v[228:231], v[8:11]
	v_mfma_f32_16x16x32_bf16 v[4:7], v[212:215], v[228:231], v[4:7]
	v_mfma_f32_16x16x32_bf16 v[0:3], v[216:219], v[228:231], v[0:3]
	s_branch .Lg_rot244_main
.Lg_rot244_first:
	v_add_u32_e32 v174, s16, v137
	s_xor_b32 s19, s18, 0x10000
	v_add_u32_e32 v176, 64, v174
	v_add_u32_e32 v179, s19, v128
	v_ashrrev_i32_e32 v177, 31, v176
	v_lshlrev_b64 v[176:177], 1, v[176:177]
	v_readfirstlane_b32 s19, v179
	v_lshl_add_u64 v[180:181], s[6:7], 0, v[176:177]
	s_mov_b32 m0, s19
	v_add_u32_e32 v182, 0x2000, v179
	global_load_lds_dwordx4 v[180:181], off
	v_subrev_u32_e32 v251, s6, v180
	v_add_u32_e32 v180, 0x10040, v174
	v_ashrrev_i32_e32 v181, 31, v180
	v_lshlrev_b64 v[180:181], 1, v[180:181]
	v_readfirstlane_b32 s19, v182
	v_lshl_add_u64 v[184:185], s[6:7], 0, v[180:181]
	s_mov_b32 m0, s19
	v_add_u32_e32 v175, 0x4000, v179
	global_load_lds_dwordx4 v[184:185], off
	v_subrev_u32_e32 v250, s6, v184
	v_add_u32_e32 v184, 0x20040, v174
	v_ashrrev_i32_e32 v185, 31, v184
	v_lshlrev_b64 v[184:185], 1, v[184:185]
	v_readfirstlane_b32 s19, v175
	v_lshl_add_u64 v[182:183], s[6:7], 0, v[184:185]
	s_mov_b32 m0, s19
	v_add_u32_e32 v187, 0x6000, v179
	global_load_lds_dwordx4 v[182:183], off
	v_subrev_u32_e32 v249, s6, v182
	v_add_u32_e32 v182, 0x30040, v174
	v_ashrrev_i32_e32 v183, 31, v182
	v_lshlrev_b64 v[182:183], 1, v[182:183]
	v_readfirstlane_b32 s19, v187
	v_lshl_add_u64 v[174:175], s[6:7], 0, v[182:183]
	s_mov_b32 m0, s19
	v_lshl_add_u64 v[176:177], s[0:1], 0, v[176:177]
	global_load_lds_dwordx4 v[174:175], off
	v_subrev_u32_e32 v248, s6, v174
	v_add_u32_e32 v174, 0x8000, v179
	s_nop 0
	v_readfirstlane_b32 s19, v174
	s_mov_b32 m0, s19
	s_nop 0
	global_load_lds_dwordx4 v[176:177], off
	v_subrev_u32_e32 v247, s0, v176
	v_lshl_add_u64 v[176:177], s[0:1], 0, v[180:181]
	v_add_u32_e32 v180, 0xa000, v179
	s_nop 0
	v_readfirstlane_b32 s19, v180
	v_add_u32_e32 v180, 0xc000, v179
	s_mov_b32 m0, s19
	v_readfirstlane_b32 s19, v180
	v_add_u32_e32 v180, 0xe000, v179
	global_load_lds_dwordx4 v[176:177], off
	v_subrev_u32_e32 v246, s0, v176
	v_lshl_add_u64 v[176:177], s[0:1], 0, v[184:185]
	s_mov_b32 m0, s19
	v_readfirstlane_b32 s19, v180
	global_load_lds_dwordx4 v[176:177], off
	v_subrev_u32_e32 v245, s0, v176
	v_lshl_add_u64 v[176:177], s[0:1], 0, v[182:183]
	s_mov_b32 m0, s19
	s_nop 0
	global_load_lds_dwordx4 v[176:177], off
	v_subrev_u32_e32 v244, s0, v176
	s_add_u32 s98, s6, 0x80
	s_addc_u32 s99, s7, 0
	s_add_u32 s100, s0, 0x80
	s_addc_u32 s101, s1, 0
	v_add_u32_e32 v154, s18, v136
	v_add_u32_e32 v178, v154, v132
	ds_read_b128 v[138:141], v178 offset:32768
	ds_read_b128 v[142:145], v178 offset:34816
	ds_read_b128 v[146:149], v178 offset:36864
	ds_read_b128 v[150:153], v178 offset:38912
	v_add_u32_e32 v186, v154, v129
	ds_read_b128 v[154:157], v186
	ds_read_b128 v[158:161], v186 offset:2048
	ds_read_b128 v[162:165], v186 offset:4096
	ds_read_b128 v[166:169], v186 offset:6144
	ds_read_b128 v[170:173], v186 offset:8192
	s_branch .Lg_rot244_main
.Lg_rot244_last:
	v_add_u32_e32 v154, s18, v136
	v_add_u32_e32 v178, v154, v132
	ds_read_b128 v[138:141], v178 offset:32768
	ds_read_b128 v[142:145], v178 offset:34816
	ds_read_b128 v[146:149], v178 offset:36864
	ds_read_b128 v[150:153], v178 offset:38912
	v_add_u32_e32 v186, v154, v129
	ds_read_b128 v[154:157], v186
	ds_read_b128 v[158:161], v186 offset:2048
	ds_read_b128 v[162:165], v186 offset:4096
	ds_read_b128 v[166:169], v186 offset:6144
	ds_read_b128 v[170:173], v186 offset:8192
	v_mfma_f32_16x16x32_bf16 v[60:63], v[188:191], v[192:195], v[60:63]
	v_mfma_f32_16x16x32_bf16 v[56:59], v[196:199], v[192:195], v[56:59]
	v_mfma_f32_16x16x32_bf16 v[52:55], v[212:215], v[192:195], v[52:55]
	v_mfma_f32_16x16x32_bf16 v[48:51], v[216:219], v[192:195], v[48:51]
	v_mfma_f32_16x16x32_bf16 v[44:47], v[188:191], v[220:223], v[44:47]
	v_mfma_f32_16x16x32_bf16 v[40:43], v[196:199], v[220:223], v[40:43]
	v_mfma_f32_16x16x32_bf16 v[36:39], v[212:215], v[220:223], v[36:39]
	v_mfma_f32_16x16x32_bf16 v[32:35], v[216:219], v[220:223], v[32:35]
	v_mfma_f32_16x16x32_bf16 v[28:31], v[188:191], v[224:227], v[28:31]
	v_mfma_f32_16x16x32_bf16 v[24:27], v[196:199], v[224:227], v[24:27]
	v_mfma_f32_16x16x32_bf16 v[20:23], v[212:215], v[224:227], v[20:23]
	v_mfma_f32_16x16x32_bf16 v[16:19], v[216:219], v[224:227], v[16:19]
	v_mfma_f32_16x16x32_bf16 v[12:15], v[188:191], v[228:231], v[12:15]
	v_mfma_f32_16x16x32_bf16 v[8:11], v[196:199], v[228:231], v[8:11]
	v_mfma_f32_16x16x32_bf16 v[4:7], v[212:215], v[228:231], v[4:7]
	v_mfma_f32_16x16x32_bf16 v[0:3], v[216:219], v[228:231], v[0:3]

; #define LDB_(dst, ks) _Pragma("unroll") for (int n = 0; n < 4; ++n) dst[n] = *(const bf16x8*)(sB + b_off + n * 2048 + (ks) * 1024)
; #define LDA_(dst, ks, h) _Pragma("unroll") for (int m = 0; m < 4; ++m) dst[m] = *(const bf16x8*)(sA + a_off + ((h) * 4 + m) * 2048 + (ks) * 1024)
; #define MMA_(A, B, h) _Pragma("unroll") for (int m = 0; m < 4; ++m) _Pragma("unroll") for (int n = 0; n < 4; ++n) \
;       acc[(h) * 4 + m][n] = SWAP ? MFMA16(B[n], A[m], acc[(h) * 4 + m][n]) : MFMA16(A[m], B[n], acc[(h) * 4 + m][n])
; template <int MF, int NF, bool SWAP = true>
; DI void gemm_main(f32x4 (&acc)[MF][NF], const u16* __restrict__ Ab, int lda, const u16* __restrict__ Bb, int ldb,
;                   int K, char* shm) {
;     ...
;   for (int t = 0; t < nt; ++t) {
;     const int cur = RING3 ? cur3 : (t & 1);
;     if constexpr (RING3) {
;       if (t + 2 < nt) G_STAGE(nxt3, t + 2);
;     } else {
;       if (t + 1 < nt) G_STAGE(cur ^ 1, t + 1);
;     }
;     const char* sA = shm + cur * STAGE;
;     const char* sB = sA + TILE_A;
;     if constexpr (MF == 8 && NF == 4) {
;       bf16x8 B0[4], B1[4], A0[4], A1[4], A2[4], A3[4];
;     ...
;       LDB_(B0, 0); LDA_(A0, 0, 0);
;       LDA_(A1, 0, 1); MMA_(A0, B0, 0);
;       LDB_(B1, 1); LDA_(A2, 1, 0); MMA_(A1, B0, 1);
;       LDA_(A3, 1, 1); MMA_(A2, B1, 0);
;       MMA_(A3, B1, 1);
.LBB0_314:
	s_and_b32 s16, s5, 0x10000
	s_cmp_gt_u32 s15, 14
	s_cbranch_scc1 .Lg_rot314_last
	s_cmp_eq_u32 s15, 0
	s_cbranch_scc1 .Lg_rot314_first
	v_mfma_f32_16x16x32_bf16 v[60:63], v[188:191], v[192:195], v[60:63]
	s_xor_b32 s17, s16, 0x10000
	v_add_u32_e32 v179, s17, v128
	v_mfma_f32_16x16x32_bf16 v[56:59], v[188:191], v[196:199], v[56:59]
	s_nop 0
	v_readfirstlane_b32 s17, v179
	s_nop 1
	s_add_u32 m0, s17, 0x0
	v_mfma_f32_16x16x32_bf16 v[52:55], v[188:191], v[212:215], v[52:55]
	global_load_lds_dwordx4 v251, s[98:99]
	s_add_u32 m0, s17, 0x2000
	v_mfma_f32_16x16x32_bf16 v[48:51], v[188:191], v[216:219], v[48:51]
	global_load_lds_dwordx4 v250, s[98:99]
	s_add_u32 m0, s17, 0x4000
	v_mfma_f32_16x16x32_bf16 v[44:47], v[220:223], v[192:195], v[44:47]
	global_load_lds_dwordx4 v249, s[98:99]
	s_add_u32 m0, s17, 0x6000
	v_mfma_f32_16x16x32_bf16 v[40:43], v[220:223], v[196:199], v[40:43]
	global_load_lds_dwordx4 v248, s[98:99]
	s_add_u32 m0, s17, 0x8000
	v_mfma_f32_16x16x32_bf16 v[36:39], v[220:223], v[212:215], v[36:39]
	global_load_lds_dwordx4 v247, s[100:101]
	s_add_u32 m0, s17, 0xa000
	v_mfma_f32_16x16x32_bf16 v[32:35], v[220:223], v[216:219], v[32:35]
	global_load_lds_dwordx4 v246, s[100:101]
	s_add_u32 m0, s17, 0xc000
	v_mfma_f32_16x16x32_bf16 v[28:31], v[224:227], v[192:195], v[28:31]
	global_load_lds_dwordx4 v245, s[100:101]
	s_add_u32 m0, s17, 0xe000
	v_mfma_f32_16x16x32_bf16 v[24:27], v[224:227], v[196:199], v[24:27]
	global_load_lds_dwordx4 v244, s[100:101]
	v_mfma_f32_16x16x32_bf16 v[20:23], v[224:227], v[212:215], v[20:23]
	s_add_u32 s98, s98, 0x80
	s_addc_u32 s99, s99, 0
	s_add_u32 s100, s100, 0x80
	s_addc_u32 s101, s101, 0
	v_add_u32_e32 v138, s16, v136
	v_add_u32_e32 v186, v138, v129
	v_add_u32_e32 v178, v138, v132
	ds_read_b128 v[138:141], v186
	ds_read_b128 v[158:161], v186 offset:2048
	ds_read_b128 v[142:145], v178 offset:32768
	ds_read_b128 v[146:149], v178 offset:34816
	ds_read_b128 v[150:153], v178 offset:36864
	ds_read_b128 v[154:157], v178 offset:38912
	ds_read_b128 v[162:165], v186 offset:4096
	ds_read_b128 v[166:169], v186 offset:6144
	ds_read_b128 v[170:173], v186 offset:8192
	v_mfma_f32_16x16x32_bf16 v[16:19], v[224:227], v[216:219], v[16:19]
	v_mfma_f32_16x16x32_bf16 v[12:15], v[228:231], v[192:195], v[12:15]
	v_mfma_f32_16x16x32_bf16 v[4:7], v[228:231], v[196:199], v[4:7]
	v_mfma_f32_16x16x32_bf16 v[0:3], v[228:231], v[212:215], v[0:3]
	v_mfma_f32_16x16x32_bf16 v[8:11], v[228:231], v[216:219], v[8:11]
	s_branch .Lg_rot314_main
.Lg_rot314_first:
	v_add_u32_e32 v174, s13, v137
	s_xor_b32 s17, s16, 0x10000
	v_add_u32_e32 v176, 64, v174
	v_add_u32_e32 v179, s17, v128
	v_ashrrev_i32_e32 v177, 31, v176
	v_lshlrev_b64 v[176:177], 1, v[176:177]
	v_readfirstlane_b32 s17, v179
	v_lshl_add_u64 v[180:181], s[6:7], 0, v[176:177]
	s_mov_b32 m0, s17
	v_add_u32_e32 v182, 0x2000, v179
	global_load_lds_dwordx4 v[180:181], off
	v_subrev_u32_e32 v251, s6, v180
	v_add_u32_e32 v180, 0x10040, v174
	v_ashrrev_i32_e32 v181, 31, v180
	v_lshlrev_b64 v[180:181], 1, v[180:181]
	v_readfirstlane_b32 s17, v182
	v_lshl_add_u64 v[184:185], s[6:7], 0, v[180:181]
	s_mov_b32 m0, s17
	v_add_u32_e32 v175, 0x4000, v179
	global_load_lds_dwordx4 v[184:185], off
	v_subrev_u32_e32 v250, s6, v184
	v_add_u32_e32 v184, 0x20040, v174
	v_ashrrev_i32_e32 v185, 31, v184
	v_lshlrev_b64 v[184:185], 1, v[184:185]
	v_readfirstlane_b32 s17, v175
	v_lshl_add_u64 v[182:183], s[6:7], 0, v[184:185]
	s_mov_b32 m0, s17
	v_add_u32_e32 v187, 0x6000, v179
	global_load_lds_dwordx4 v[182:183], off
	v_subrev_u32_e32 v249, s6, v182
	v_add_u32_e32 v182, 0x30040, v174
	v_ashrrev_i32_e32 v183, 31, v182
	v_lshlrev_b64 v[182:183], 1, v[182:183]
	v_readfirstlane_b32 s17, v187
	v_lshl_add_u64 v[174:175], s[6:7], 0, v[182:183]
	s_mov_b32 m0, s17
	v_lshl_add_u64 v[176:177], s[0:1], 0, v[176:177]
	global_load_lds_dwordx4 v[174:175], off
	v_subrev_u32_e32 v248, s6, v174
	v_add_u32_e32 v174, 0x8000, v179
	s_nop 0
	v_readfirstlane_b32 s17, v174
	s_mov_b32 m0, s17
	s_nop 0
	global_load_lds_dwordx4 v[176:177], off
	v_subrev_u32_e32 v247, s0, v176
	v_lshl_add_u64 v[176:177], s[0:1], 0, v[180:181]
	v_add_u32_e32 v180, 0xa000, v179
	s_nop 0
	v_readfirstlane_b32 s17, v180
	v_add_u32_e32 v180, 0xc000, v179
	s_mov_b32 m0, s17
	v_readfirstlane_b32 s17, v180
	v_add_u32_e32 v180, 0xe000, v179
	global_load_lds_dwordx4 v[176:177], off
	v_subrev_u32_e32 v246, s0, v176
	v_lshl_add_u64 v[176:177], s[0:1], 0, v[184:185]
	s_mov_b32 m0, s17
	v_readfirstlane_b32 s17, v180
	global_load_lds_dwordx4 v[176:177], off
	v_subrev_u32_e32 v245, s0, v176
	v_lshl_add_u64 v[176:177], s[0:1], 0, v[182:183]
	s_mov_b32 m0, s17
	s_nop 0
	global_load_lds_dwordx4 v[176:177], off
	v_subrev_u32_e32 v244, s0, v176
	s_add_u32 s98, s6, 0x80
	s_addc_u32 s99, s7, 0
	s_add_u32 s100, s0, 0x80
	s_addc_u32 s101, s1, 0
	v_add_u32_e32 v138, s16, v136
	v_add_u32_e32 v186, v138, v129
	v_add_u32_e32 v178, v138, v132
	ds_read_b128 v[138:141], v186
	ds_read_b128 v[158:161], v186 offset:2048
	ds_read_b128 v[142:145], v178 offset:32768
	ds_read_b128 v[146:149], v178 offset:34816
	ds_read_b128 v[150:153], v178 offset:36864
	ds_read_b128 v[154:157], v178 offset:38912
	ds_read_b128 v[162:165], v186 offset:4096
	ds_read_b128 v[166:169], v186 offset:6144
	ds_read_b128 v[170:173], v186 offset:8192
	s_branch .Lg_rot314_main
.Lg_rot314_last:
	v_add_u32_e32 v138, s16, v136
	v_add_u32_e32 v186, v138, v129
	v_add_u32_e32 v178, v138, v132
	ds_read_b128 v[138:141], v186
	ds_read_b128 v[158:161], v186 offset:2048
	ds_read_b128 v[142:145], v178 offset:32768
	ds_read_b128 v[146:149], v178 offset:34816
	ds_read_b128 v[150:153], v178 offset:36864
	ds_read_b128 v[154:157], v178 offset:38912
	ds_read_b128 v[162:165], v186 offset:4096
	ds_read_b128 v[166:169], v186 offset:6144
	ds_read_b128 v[170:173], v186 offset:8192
	v_mfma_f32_16x16x32_bf16 v[60:63], v[188:191], v[192:195], v[60:63]
	v_mfma_f32_16x16x32_bf16 v[56:59], v[188:191], v[196:199], v[56:59]
	v_mfma_f32_16x16x32_bf16 v[52:55], v[188:191], v[212:215], v[52:55]
	v_mfma_f32_16x16x32_bf16 v[48:51], v[188:191], v[216:219], v[48:51]
	v_mfma_f32_16x16x32_bf16 v[44:47], v[220:223], v[192:195], v[44:47]
	v_mfma_f32_16x16x32_bf16 v[40:43], v[220:223], v[196:199], v[40:43]
	v_mfma_f32_16x16x32_bf16 v[36:39], v[220:223], v[212:215], v[36:39]
	v_mfma_f32_16x16x32_bf16 v[32:35], v[220:223], v[216:219], v[32:35]
	v_mfma_f32_16x16x32_bf16 v[28:31], v[224:227], v[192:195], v[28:31]
	v_mfma_f32_16x16x32_bf16 v[24:27], v[224:227], v[196:199], v[24:27]
	v_mfma_f32_16x16x32_bf16 v[20:23], v[224:227], v[212:215], v[20:23]
	v_mfma_f32_16x16x32_bf16 v[16:19], v[224:227], v[216:219], v[16:19]
	v_mfma_f32_16x16x32_bf16 v[12:15], v[228:231], v[192:195], v[12:15]
	v_mfma_f32_16x16x32_bf16 v[4:7], v[228:231], v[196:199], v[4:7]
	v_mfma_f32_16x16x32_bf16 v[0:3], v[228:231], v[212:215], v[0:3]
	v_mfma_f32_16x16x32_bf16 v[8:11], v[228:231], v[216:219], v[8:11]

; #define LDB_(dst, ks) _Pragma("unroll") for (int n = 0; n < 4; ++n) dst[n] = *(const bf16x8*)(sB + b_off + n * 2048 + (ks) * 1024)
; #define LDA_(dst, ks, h) _Pragma("unroll") for (int m = 0; m < 4; ++m) dst[m] = *(const bf16x8*)(sA + a_off + ((h) * 4 + m) * 2048 + (ks) * 1024)
; #define MMA_(A, B, h) _Pragma("unroll") for (int m = 0; m < 4; ++m) _Pragma("unroll") for (int n = 0; n < 4; ++n) \
;       acc[(h) * 4 + m][n] = SWAP ? MFMA16(B[n], A[m], acc[(h) * 4 + m][n]) : MFMA16(A[m], B[n], acc[(h) * 4 + m][n])
; template <int MF, int NF, bool SWAP = true>
; DI void gemm_main(f32x4 (&acc)[MF][NF], const u16* __restrict__ Ab, int lda, const u16* __restrict__ Bb, int ldb,
;                   int K, char* shm) {
;     ...
;   for (int t = 0; t < nt; ++t) {
;     const int cur = RING3 ? cur3 : (t & 1);
;     if constexpr (RING3) {
;       if (t + 2 < nt) G_STAGE(nxt3, t + 2);
;     } else {
;       if (t + 1 < nt) G_STAGE(cur ^ 1, t + 1);
;     }
;     const char* sA = shm + cur * STAGE;
;     const char* sB = sA + TILE_A;
;     if constexpr (MF == 8 && NF == 4) {
;       bf16x8 B0[4], B1[4], A0[4], A1[4], A2[4], A3[4];
;     ...
;       LDB_(B0, 0); LDA_(A0, 0, 0);
;       LDA_(A1, 0, 1); MMA_(A0, B0, 0);
;       LDB_(B1, 1); LDA_(A2, 1, 0); MMA_(A1, B0, 1);
;       LDA_(A3, 1, 1); MMA_(A2, B1, 0);
;       MMA_(A3, B1, 1);
.LBB0_553:
	s_and_b32 s21, s18, 0x10000
	s_cmp_gt_u32 s20, 2
	s_cbranch_scc1 .Lg_rot553_last
	s_cmp_eq_u32 s20, 0
	s_cbranch_scc1 .Lg_rot553_first
	v_mfma_f32_16x16x32_bf16 v[60:63], v[196:199], v[212:215], v[60:63]
	s_xor_b32 s22, s21, 0x10000
	v_add_u32_e32 v195, s22, v132
	v_mfma_f32_16x16x32_bf16 v[56:59], v[216:219], v[212:215], v[56:59]
	s_nop 0
	v_readfirstlane_b32 s22, v195
	s_nop 1
	s_add_u32 m0, s22, 0x0
	v_mfma_f32_16x16x32_bf16 v[52:55], v[220:223], v[212:215], v[52:55]
	global_load_lds_dwordx4 v251, s[98:99]
	s_add_u32 m0, s22, 0x2000
	v_mfma_f32_16x16x32_bf16 v[48:51], v[224:227], v[212:215], v[48:51]
	global_load_lds_dwordx4 v250, s[98:99]
	s_add_u32 m0, s22, 0x4000
	v_mfma_f32_16x16x32_bf16 v[44:47], v[196:199], v[228:231], v[44:47]
	global_load_lds_dwordx4 v249, s[98:99]
	s_add_u32 m0, s22, 0x6000
	v_mfma_f32_16x16x32_bf16 v[40:43], v[216:219], v[228:231], v[40:43]
	global_load_lds_dwordx4 v248, s[98:99]
	s_add_u32 m0, s22, 0x8000
	v_mfma_f32_16x16x32_bf16 v[36:39], v[220:223], v[228:231], v[36:39]
	global_load_lds_dwordx4 v247, s[100:101]
	s_add_u32 m0, s22, 0xa000
	v_mfma_f32_16x16x32_bf16 v[32:35], v[224:227], v[228:231], v[32:35]
	global_load_lds_dwordx4 v246, s[100:101]
	s_add_u32 m0, s22, 0xc000
	v_mfma_f32_16x16x32_bf16 v[28:31], v[196:199], v[232:235], v[28:31]
	global_load_lds_dwordx4 v245, s[100:101]
	s_add_u32 m0, s22, 0xe000
	v_mfma_f32_16x16x32_bf16 v[24:27], v[216:219], v[232:235], v[24:27]
	global_load_lds_dwordx4 v244, s[100:101]
	v_mfma_f32_16x16x32_bf16 v[20:23], v[220:223], v[232:235], v[20:23]
	s_add_u32 s98, s98, 0x80
	s_addc_u32 s99, s99, 0
	s_add_u32 s100, s100, 0x80
	s_addc_u32 s101, s101, 0
	v_add_u32_e32 v162, s21, v143
	v_add_u32_e32 v186, v162, v142
	ds_read_b128 v[146:149], v186 offset:32768
	ds_read_b128 v[150:153], v186 offset:34816
	ds_read_b128 v[154:157], v186 offset:36864
	ds_read_b128 v[158:161], v186 offset:38912
	v_add_u32_e32 v194, v162, v141
	ds_read_b128 v[162:165], v194
	ds_read_b128 v[166:169], v194 offset:2048
	ds_read_b128 v[170:173], v194 offset:4096
	ds_read_b128 v[174:177], v194 offset:6144
	ds_read_b128 v[178:181], v194 offset:8192
	v_mfma_f32_16x16x32_bf16 v[16:19], v[224:227], v[232:235], v[16:19]
	v_mfma_f32_16x16x32_bf16 v[12:15], v[196:199], v[236:239], v[12:15]
	v_mfma_f32_16x16x32_bf16 v[4:7], v[216:219], v[236:239], v[4:7]
	v_mfma_f32_16x16x32_bf16 v[0:3], v[220:223], v[236:239], v[0:3]
	v_mfma_f32_16x16x32_bf16 v[8:11], v[224:227], v[236:239], v[8:11]
	s_branch .Lg_rot553_main
.Lg_rot553_first:
	s_xor_b32 s22, s21, 0x10000
	v_add_u32_e32 v187, s19, v145
	v_add_u32_e32 v195, s22, v132
	v_add_u32_e32 v182, 64, v187
	v_ashrrev_i32_e32 v183, 31, v182
	v_readfirstlane_b32 s22, v195
	v_lshl_add_u64 v[182:183], v[182:183], 1, s[4:5]
	s_mov_b32 m0, s22
	v_add_u32_e32 v211, 0x2000, v195
	global_load_lds_dwordx4 v[182:183], off
	v_subrev_u32_e32 v251, s4, v182
	v_add_u32_e32 v182, 0x7040, v187
	v_ashrrev_i32_e32 v183, 31, v182
	v_readfirstlane_b32 s22, v211
	v_lshl_add_u64 v[182:183], v[182:183], 1, s[4:5]
	s_mov_b32 m0, s22
	v_add_u32_e32 v211, 0x4000, v195
	global_load_lds_dwordx4 v[182:183], off
	v_subrev_u32_e32 v250, s4, v182
	v_add_u32_e32 v182, 0xe040, v187
	v_ashrrev_i32_e32 v183, 31, v182
	v_readfirstlane_b32 s22, v211
	v_lshl_add_u64 v[182:183], v[182:183], 1, s[4:5]
	s_mov_b32 m0, s22
	v_add_u32_e32 v211, s19, v144
	global_load_lds_dwordx4 v[182:183], off
	v_subrev_u32_e32 v249, s4, v182
	v_add_u32_e32 v182, 0x15040, v187
	v_add_u32_e32 v187, 0x6000, v195
	v_ashrrev_i32_e32 v183, 31, v182
	v_readfirstlane_b32 s22, v187
	v_lshl_add_u64 v[182:183], v[182:183], 1, s[4:5]
	s_mov_b32 m0, s22
	v_add_u32_e32 v187, 0x8000, v195
	global_load_lds_dwordx4 v[182:183], off
	v_subrev_u32_e32 v248, s4, v182
	v_add_u32_e32 v182, 64, v211
	v_ashrrev_i32_e32 v183, 31, v182
	v_readfirstlane_b32 s22, v187
	v_lshl_add_u64 v[182:183], v[182:183], 1, s[6:7]
	s_mov_b32 m0, s22
	v_add_u32_e32 v187, 0xa000, v195
	global_load_lds_dwordx4 v[182:183], off
	v_subrev_u32_e32 v247, s6, v182
	v_add_u32_e32 v182, 0x4040, v211
	v_ashrrev_i32_e32 v183, 31, v182
	v_readfirstlane_b32 s22, v187
	v_lshl_add_u64 v[182:183], v[182:183], 1, s[6:7]
	s_mov_b32 m0, s22
	v_add_u32_e32 v187, 0xc000, v195
	global_load_lds_dwordx4 v[182:183], off
	v_subrev_u32_e32 v246, s6, v182
	v_add_u32_e32 v182, 0x8040, v211
	v_ashrrev_i32_e32 v183, 31, v182
	v_readfirstlane_b32 s22, v187
	v_lshl_add_u64 v[182:183], v[182:183], 1, s[6:7]
	s_mov_b32 m0, s22
	v_add_u32_e32 v195, 0xe000, v195
	global_load_lds_dwordx4 v[182:183], off
	v_subrev_u32_e32 v245, s6, v182
	v_add_u32_e32 v182, 0xc040, v211
	v_ashrrev_i32_e32 v183, 31, v182
	v_readfirstlane_b32 s22, v195
	v_lshl_add_u64 v[182:183], v[182:183], 1, s[6:7]
	s_mov_b32 m0, s22
	s_nop 0
	global_load_lds_dwordx4 v[182:183], off
	v_subrev_u32_e32 v244, s6, v182
	s_add_u32 s98, s4, 0x80
	s_addc_u32 s99, s5, 0
	s_add_u32 s100, s6, 0x80
	s_addc_u32 s101, s7, 0
	v_add_u32_e32 v162, s21, v143
	v_add_u32_e32 v186, v162, v142
	ds_read_b128 v[146:149], v186 offset:32768
	ds_read_b128 v[150:153], v186 offset:34816
	ds_read_b128 v[154:157], v186 offset:36864
	ds_read_b128 v[158:161], v186 offset:38912
	v_add_u32_e32 v194, v162, v141
	ds_read_b128 v[162:165], v194
	ds_read_b128 v[166:169], v194 offset:2048
	ds_read_b128 v[170:173], v194 offset:4096
	ds_read_b128 v[174:177], v194 offset:6144
	ds_read_b128 v[178:181], v194 offset:8192
	s_branch .Lg_rot553_main
.Lg_rot553_last:
	v_add_u32_e32 v162, s21, v143
	v_add_u32_e32 v186, v162, v142
	ds_read_b128 v[146:149], v186 offset:32768
	ds_read_b128 v[150:153], v186 offset:34816
	ds_read_b128 v[154:157], v186 offset:36864
	ds_read_b128 v[158:161], v186 offset:38912
	v_add_u32_e32 v194, v162, v141
	ds_read_b128 v[162:165], v194
	ds_read_b128 v[166:169], v194 offset:2048
	ds_read_b128 v[170:173], v194 offset:4096
	ds_read_b128 v[174:177], v194 offset:6144
	ds_read_b128 v[178:181], v194 offset:8192
	v_mfma_f32_16x16x32_bf16 v[60:63], v[196:199], v[212:215], v[60:63]
	v_mfma_f32_16x16x32_bf16 v[56:59], v[216:219], v[212:215], v[56:59]
	v_mfma_f32_16x16x32_bf16 v[52:55], v[220:223], v[212:215], v[52:55]
	v_mfma_f32_16x16x32_bf16 v[48:51], v[224:227], v[212:215], v[48:51]
	v_mfma_f32_16x16x32_bf16 v[44:47], v[196:199], v[228:231], v[44:47]
	v_mfma_f32_16x16x32_bf16 v[40:43], v[216:219], v[228:231], v[40:43]
	v_mfma_f32_16x16x32_bf16 v[36:39], v[220:223], v[228:231], v[36:39]
	v_mfma_f32_16x16x32_bf16 v[32:35], v[224:227], v[228:231], v[32:35]
	v_mfma_f32_16x16x32_bf16 v[28:31], v[196:199], v[232:235], v[28:31]
	v_mfma_f32_16x16x32_bf16 v[24:27], v[216:219], v[232:235], v[24:27]
	v_mfma_f32_16x16x32_bf16 v[20:23], v[220:223], v[232:235], v[20:23]
	v_mfma_f32_16x16x32_bf16 v[16:19], v[224:227], v[232:235], v[16:19]
	v_mfma_f32_16x16x32_bf16 v[12:15], v[196:199], v[236:239], v[12:15]
	v_mfma_f32_16x16x32_bf16 v[4:7], v[216:219], v[236:239], v[4:7]
	v_mfma_f32_16x16x32_bf16 v[0:3], v[220:223], v[236:239], v[0:3]
	v_mfma_f32_16x16x32_bf16 v[8:11], v[224:227], v[236:239], v[8:11]

; #define LDB_(dst, ks) _Pragma("unroll") for (int n = 0; n < 4; ++n) dst[n] = *(const bf16x8*)(sB + b_off + n * 2048 + (ks) * 1024)
; #define LDA_(dst, ks, h) _Pragma("unroll") for (int m = 0; m < 4; ++m) dst[m] = *(const bf16x8*)(sA + a_off + ((h) * 4 + m) * 2048 + (ks) * 1024)
; #define MMA_(A, B, h) _Pragma("unroll") for (int m = 0; m < 4; ++m) _Pragma("unroll") for (int n = 0; n < 4; ++n) \
;       acc[(h) * 4 + m][n] = SWAP ? MFMA16(B[n], A[m], acc[(h) * 4 + m][n]) : MFMA16(A[m], B[n], acc[(h) * 4 + m][n])
; template <int MF, int NF, bool SWAP = true>
; DI void gemm_main(f32x4 (&acc)[MF][NF], const u16* __restrict__ Ab, int lda, const u16* __restrict__ Bb, int ldb,
;                   int K, char* shm) {
;     ...
;   for (int t = 0; t < nt; ++t) {
;     const int cur = RING3 ? cur3 : (t & 1);
;     if constexpr (RING3) {
;       if (t + 2 < nt) G_STAGE(nxt3, t + 2);
;     } else {
;       if (t + 1 < nt) G_STAGE(cur ^ 1, t + 1);
;     }
;     const char* sA = shm + cur * STAGE;
;     const char* sB = sA + TILE_A;
;     if constexpr (MF == 8 && NF == 4) {
;       bf16x8 B0[4], B1[4], A0[4], A1[4], A2[4], A3[4];
;     ...
;       LDB_(B0, 0); LDA_(A0, 0, 0);
;       LDA_(A1, 0, 1); MMA_(A0, B0, 0);
;       LDB_(B1, 1); LDA_(A2, 1, 0); MMA_(A1, B0, 1);
;       LDA_(A3, 1, 1); MMA_(A2, B1, 0);
;       MMA_(A3, B1, 1);
.LBB0_589:
	s_and_b32 s21, s16, 0x10000
	s_cmp_gt_u32 s15, 14
	s_cbranch_scc1 .Lg_rot589_last
	s_cmp_eq_u32 s15, 0
	s_cbranch_scc1 .Lg_rot589_first
	v_mfma_f32_16x16x32_bf16 v[60:63], v[186:189], v[190:193], v[60:63]
	s_xor_b32 s22, s21, 0x10000
	v_add_u32_e32 v179, s22, v128
	v_mfma_f32_16x16x32_bf16 v[56:59], v[194:197], v[190:193], v[56:59]
	s_nop 0
	v_readfirstlane_b32 s22, v179
	s_nop 1
	s_add_u32 m0, s22, 0x0
	v_mfma_f32_16x16x32_bf16 v[52:55], v[198:201], v[190:193], v[52:55]
	global_load_lds_dwordx4 v251, s[98:99]
	s_add_u32 m0, s22, 0x2000
	v_mfma_f32_16x16x32_bf16 v[48:51], v[218:221], v[190:193], v[48:51]
	global_load_lds_dwordx4 v250, s[98:99]
	s_add_u32 m0, s22, 0x4000
	v_mfma_f32_16x16x32_bf16 v[44:47], v[186:189], v[222:225], v[44:47]
	global_load_lds_dwordx4 v249, s[98:99]
	s_add_u32 m0, s22, 0x6000
	v_mfma_f32_16x16x32_bf16 v[40:43], v[194:197], v[222:225], v[40:43]
	global_load_lds_dwordx4 v248, s[98:99]
	s_add_u32 m0, s22, 0x8000
	v_mfma_f32_16x16x32_bf16 v[36:39], v[198:201], v[222:225], v[36:39]
	global_load_lds_dwordx4 v247, s[100:101]
	s_add_u32 m0, s22, 0xa000
	v_mfma_f32_16x16x32_bf16 v[32:35], v[218:221], v[222:225], v[32:35]
	global_load_lds_dwordx4 v246, s[100:101]
	s_add_u32 m0, s22, 0xc000
	v_mfma_f32_16x16x32_bf16 v[28:31], v[186:189], v[226:229], v[28:31]
	global_load_lds_dwordx4 v245, s[100:101]
	s_add_u32 m0, s22, 0xe000
	v_mfma_f32_16x16x32_bf16 v[24:27], v[194:197], v[226:229], v[24:27]
	global_load_lds_dwordx4 v244, s[100:101]
	v_mfma_f32_16x16x32_bf16 v[20:23], v[198:201], v[226:229], v[20:23]
	s_add_u32 s98, s98, 0x80
	s_addc_u32 s99, s99, 0
	s_add_u32 s100, s100, 0x80
	s_addc_u32 s101, s101, 0
	v_add_u32_e32 v137, s21, v132
	v_add_u32_e32 v178, v137, v131
	ds_read_b128 v[138:141], v178 offset:32768
	ds_read_b128 v[142:145], v178 offset:34816
	ds_read_b128 v[146:149], v178 offset:36864
	ds_read_b128 v[150:153], v178 offset:38912
	v_add_u32_e32 v137, v137, v129
	ds_read_b128 v[154:157], v137
	ds_read_b128 v[158:161], v137 offset:2048
	ds_read_b128 v[162:165], v137 offset:4096
	ds_read_b128 v[166:169], v137 offset:6144
	ds_read_b128 v[170:173], v137 offset:8192
	v_mfma_f32_16x16x32_bf16 v[16:19], v[218:221], v[226:229], v[16:19]
	v_mfma_f32_16x16x32_bf16 v[12:15], v[186:189], v[230:233], v[12:15]
	v_mfma_f32_16x16x32_bf16 v[8:11], v[194:197], v[230:233], v[8:11]
	v_mfma_f32_16x16x32_bf16 v[4:7], v[198:201], v[230:233], v[4:7]
	v_mfma_f32_16x16x32_bf16 v[0:3], v[218:221], v[230:233], v[0:3]
	s_branch .Lg_rot589_main
.Lg_rot589_first:
	v_add_u32_e32 v174, s13, v136
	s_xor_b32 s22, s21, 0x10000
	v_add_u32_e32 v176, 64, v174
	v_add_u32_e32 v179, s22, v128
	v_ashrrev_i32_e32 v177, 31, v176
	v_lshlrev_b64 v[176:177], 1, v[176:177]
	v_readfirstlane_b32 s22, v179
	v_lshl_add_u64 v[180:181], s[0:1], 0, v[176:177]
	s_mov_b32 m0, s22
	v_add_u32_e32 v182, 0x2000, v179
	global_load_lds_dwordx4 v[180:181], off
	v_subrev_u32_e32 v251, s0, v180
	v_add_u32_e32 v180, 0x10040, v174
	v_ashrrev_i32_e32 v181, 31, v180
	v_lshlrev_b64 v[180:181], 1, v[180:181]
	v_readfirstlane_b32 s22, v182
	v_lshl_add_u64 v[184:185], s[0:1], 0, v[180:181]
	s_mov_b32 m0, s22
	v_add_u32_e32 v175, 0x4000, v179
	global_load_lds_dwordx4 v[184:185], off
	v_subrev_u32_e32 v250, s0, v184
	v_add_u32_e32 v184, 0x20040, v174
	v_ashrrev_i32_e32 v185, 31, v184
	v_lshlrev_b64 v[184:185], 1, v[184:185]
	v_readfirstlane_b32 s22, v175
	v_lshl_add_u64 v[182:183], s[0:1], 0, v[184:185]
	s_mov_b32 m0, s22
	v_add_u32_e32 v217, 0x6000, v179
	global_load_lds_dwordx4 v[182:183], off
	v_subrev_u32_e32 v249, s0, v182
	v_add_u32_e32 v182, 0x30040, v174
	v_ashrrev_i32_e32 v183, 31, v182
	v_lshlrev_b64 v[182:183], 1, v[182:183]
	v_readfirstlane_b32 s22, v217
	v_lshl_add_u64 v[174:175], s[0:1], 0, v[182:183]
	s_mov_b32 m0, s22
	v_lshl_add_u64 v[176:177], s[4:5], 0, v[176:177]
	global_load_lds_dwordx4 v[174:175], off
	v_subrev_u32_e32 v248, s0, v174
	v_add_u32_e32 v174, 0x8000, v179
	s_nop 0
	v_readfirstlane_b32 s22, v174
	s_mov_b32 m0, s22
	s_nop 0
	global_load_lds_dwordx4 v[176:177], off
	v_subrev_u32_e32 v247, s4, v176
	v_lshl_add_u64 v[176:177], s[4:5], 0, v[180:181]
	v_add_u32_e32 v180, 0xa000, v179
	s_nop 0
	v_readfirstlane_b32 s22, v180
	v_add_u32_e32 v180, 0xc000, v179
	s_mov_b32 m0, s22
	v_readfirstlane_b32 s22, v180
	v_add_u32_e32 v179, 0xe000, v179
	global_load_lds_dwordx4 v[176:177], off
	v_subrev_u32_e32 v246, s4, v176
	v_lshl_add_u64 v[176:177], s[4:5], 0, v[184:185]
	s_mov_b32 m0, s22
	v_readfirstlane_b32 s22, v179
	global_load_lds_dwordx4 v[176:177], off
	v_subrev_u32_e32 v245, s4, v176
	v_lshl_add_u64 v[176:177], s[4:5], 0, v[182:183]
	s_mov_b32 m0, s22
	s_nop 0
	global_load_lds_dwordx4 v[176:177], off
	v_subrev_u32_e32 v244, s4, v176
	s_add_u32 s98, s0, 0x80
	s_addc_u32 s99, s1, 0
	s_add_u32 s100, s4, 0x80
	s_addc_u32 s101, s5, 0
	v_add_u32_e32 v137, s21, v132
	v_add_u32_e32 v178, v137, v131
	ds_read_b128 v[138:141], v178 offset:32768
	ds_read_b128 v[142:145], v178 offset:34816
	ds_read_b128 v[146:149], v178 offset:36864
	ds_read_b128 v[150:153], v178 offset:38912
	v_add_u32_e32 v137, v137, v129
	ds_read_b128 v[154:157], v137
	ds_read_b128 v[158:161], v137 offset:2048
	ds_read_b128 v[162:165], v137 offset:4096
	ds_read_b128 v[166:169], v137 offset:6144
	ds_read_b128 v[170:173], v137 offset:8192
	s_branch .Lg_rot589_main
.Lg_rot589_last:
	v_add_u32_e32 v137, s21, v132
	v_add_u32_e32 v178, v137, v131
	ds_read_b128 v[138:141], v178 offset:32768
	ds_read_b128 v[142:145], v178 offset:34816
	ds_read_b128 v[146:149], v178 offset:36864
	ds_read_b128 v[150:153], v178 offset:38912
	v_add_u32_e32 v137, v137, v129
	ds_read_b128 v[154:157], v137
	ds_read_b128 v[158:161], v137 offset:2048
	ds_read_b128 v[162:165], v137 offset:4096
	ds_read_b128 v[166:169], v137 offset:6144
	ds_read_b128 v[170:173], v137 offset:8192
	v_mfma_f32_16x16x32_bf16 v[60:63], v[186:189], v[190:193], v[60:63]
	v_mfma_f32_16x16x32_bf16 v[56:59], v[194:197], v[190:193], v[56:59]
	v_mfma_f32_16x16x32_bf16 v[52:55], v[198:201], v[190:193], v[52:55]
	v_mfma_f32_16x16x32_bf16 v[48:51], v[218:221], v[190:193], v[48:51]
	v_mfma_f32_16x16x32_bf16 v[44:47], v[186:189], v[222:225], v[44:47]
	v_mfma_f32_16x16x32_bf16 v[40:43], v[194:197], v[222:225], v[40:43]
	v_mfma_f32_16x16x32_bf16 v[36:39], v[198:201], v[222:225], v[36:39]
	v_mfma_f32_16x16x32_bf16 v[32:35], v[218:221], v[222:225], v[32:35]
	v_mfma_f32_16x16x32_bf16 v[28:31], v[186:189], v[226:229], v[28:31]
	v_mfma_f32_16x16x32_bf16 v[24:27], v[194:197], v[226:229], v[24:27]
	v_mfma_f32_16x16x32_bf16 v[20:23], v[198:201], v[226:229], v[20:23]
	v_mfma_f32_16x16x32_bf16 v[16:19], v[218:221], v[226:229], v[16:19]
	v_mfma_f32_16x16x32_bf16 v[12:15], v[186:189], v[230:233], v[12:15]
	v_mfma_f32_16x16x32_bf16 v[8:11], v[194:197], v[230:233], v[8:11]
	v_mfma_f32_16x16x32_bf16 v[4:7], v[198:201], v[230:233], v[4:7]
	v_mfma_f32_16x16x32_bf16 v[0:3], v[218:221], v[230:233], v[0:3]

; #define LDB_(dst, ks) _Pragma("unroll") for (int n = 0; n < 4; ++n) dst[n] = *(const bf16x8*)(sB + b_off + n * 2048 + (ks) * 1024)
; #define LDA_(dst, ks, h) _Pragma("unroll") for (int m = 0; m < 4; ++m) dst[m] = *(const bf16x8*)(sA + a_off + ((h) * 4 + m) * 2048 + (ks) * 1024)
; #define MMA_(A, B, h) _Pragma("unroll") for (int m = 0; m < 4; ++m) _Pragma("unroll") for (int n = 0; n < 4; ++n) \
;       acc[(h) * 4 + m][n] = SWAP ? MFMA16(B[n], A[m], acc[(h) * 4 + m][n]) : MFMA16(A[m], B[n], acc[(h) * 4 + m][n])
; template <int MF, int NF, bool SWAP = true>
; DI void gemm_main(f32x4 (&acc)[MF][NF], const u16* __restrict__ Ab, int lda, const u16* __restrict__ Bb, int ldb,
;                   int K, char* shm) {
;     ...
;   for (int t = 0; t < nt; ++t) {
;     const int cur = RING3 ? cur3 : (t & 1);
;     if constexpr (RING3) {
;       if (t + 2 < nt) G_STAGE(nxt3, t + 2);
;     } else {
;       if (t + 1 < nt) G_STAGE(cur ^ 1, t + 1);
;     }
;     const char* sA = shm + cur * STAGE;
;     const char* sB = sA + TILE_A;
;     if constexpr (MF == 8 && NF == 4) {
;       bf16x8 B0[4], B1[4], A0[4], A1[4], A2[4], A3[4];
;     ...
;       LDB_(B0, 0); LDA_(A0, 0, 0);
;       LDA_(A1, 0, 1); MMA_(A0, B0, 0);
;       LDB_(B1, 1); LDA_(A2, 1, 0); MMA_(A1, B0, 1);
;       LDA_(A3, 1, 1); MMA_(A2, B1, 0);
;       MMA_(A3, B1, 1);
.LBB0_819:
	s_and_b32 s19, s17, 0x10000
	s_cmp_gt_u32 s18, 2
	s_cbranch_scc1 .Lg_rot819_last
	s_cmp_eq_u32 s18, 0
	s_cbranch_scc1 .Lg_rot819_first
	v_mfma_f32_16x16x32_bf16 v[60:63], v[186:189], v[190:193], v[60:63]
	s_xor_b32 s20, s19, 0x10000
	v_add_u32_e32 v179, s20, v129
	v_mfma_f32_16x16x32_bf16 v[56:59], v[194:197], v[190:193], v[56:59]
	s_nop 0
	v_readfirstlane_b32 s20, v179
	s_nop 1
	s_add_u32 m0, s20, 0x0
	v_mfma_f32_16x16x32_bf16 v[52:55], v[198:201], v[190:193], v[52:55]
	global_load_lds_dwordx4 v251, s[98:99]
	s_add_u32 m0, s20, 0x2000
	v_mfma_f32_16x16x32_bf16 v[48:51], v[218:221], v[190:193], v[48:51]
	global_load_lds_dwordx4 v250, s[98:99]
	s_add_u32 m0, s20, 0x4000
	v_mfma_f32_16x16x32_bf16 v[44:47], v[186:189], v[222:225], v[44:47]
	global_load_lds_dwordx4 v249, s[98:99]
	s_add_u32 m0, s20, 0x6000
	v_mfma_f32_16x16x32_bf16 v[40:43], v[194:197], v[222:225], v[40:43]
	global_load_lds_dwordx4 v248, s[98:99]
	s_add_u32 m0, s20, 0x8000
	v_mfma_f32_16x16x32_bf16 v[36:39], v[198:201], v[222:225], v[36:39]
	global_load_lds_dwordx4 v247, s[100:101]
	s_add_u32 m0, s20, 0xa000
	v_mfma_f32_16x16x32_bf16 v[32:35], v[218:221], v[222:225], v[32:35]
	global_load_lds_dwordx4 v246, s[100:101]
	s_add_u32 m0, s20, 0xc000
	v_mfma_f32_16x16x32_bf16 v[28:31], v[186:189], v[226:229], v[28:31]
	global_load_lds_dwordx4 v245, s[100:101]
	s_add_u32 m0, s20, 0xe000
	v_mfma_f32_16x16x32_bf16 v[24:27], v[194:197], v[226:229], v[24:27]
	global_load_lds_dwordx4 v244, s[100:101]
	v_mfma_f32_16x16x32_bf16 v[20:23], v[198:201], v[226:229], v[20:23]
	s_add_u32 s98, s98, 0x80
	s_addc_u32 s99, s99, 0
	s_add_u32 s100, s100, 0x80
	s_addc_u32 s101, s101, 0
	v_add_u32_e32 v137, s19, v132
	v_add_u32_e32 v178, v137, v131
	ds_read_b128 v[138:141], v178 offset:32768
	ds_read_b128 v[142:145], v178 offset:34816
	ds_read_b128 v[146:149], v178 offset:36864
	ds_read_b128 v[150:153], v178 offset:38912
	v_add_u32_e32 v137, v137, v130
	ds_read_b128 v[154:157], v137
	ds_read_b128 v[158:161], v137 offset:2048
	ds_read_b128 v[162:165], v137 offset:4096
	ds_read_b128 v[166:169], v137 offset:6144
	ds_read_b128 v[170:173], v137 offset:8192
	v_mfma_f32_16x16x32_bf16 v[16:19], v[218:221], v[226:229], v[16:19]
	v_mfma_f32_16x16x32_bf16 v[8:11], v[186:189], v[230:233], v[8:11]
	v_mfma_f32_16x16x32_bf16 v[4:7], v[194:197], v[230:233], v[4:7]
	v_mfma_f32_16x16x32_bf16 v[0:3], v[198:201], v[230:233], v[0:3]
	v_mfma_f32_16x16x32_bf16 v[12:15], v[218:221], v[230:233], v[12:15]
	s_branch .Lg_rot819_main
.Lg_rot819_first:
	v_add_u32_e32 v174, s1, v136
	s_xor_b32 s20, s19, 0x10000
	v_add_u32_e32 v176, 64, v174
	v_add_u32_e32 v179, s20, v129
	v_ashrrev_i32_e32 v177, 31, v176
	v_lshlrev_b64 v[176:177], 1, v[176:177]
	v_readfirstlane_b32 s20, v179
	v_lshl_add_u64 v[180:181], s[6:7], 0, v[176:177]
	s_mov_b32 m0, s20
	v_add_u32_e32 v182, 0x2000, v179
	global_load_lds_dwordx4 v[180:181], off
	v_subrev_u32_e32 v251, s6, v180
	v_add_u32_e32 v180, 0x8040, v174
	v_ashrrev_i32_e32 v181, 31, v180
	v_lshlrev_b64 v[180:181], 1, v[180:181]
	v_readfirstlane_b32 s20, v182
	v_lshl_add_u64 v[184:185], s[6:7], 0, v[180:181]
	s_mov_b32 m0, s20
	v_add_u32_e32 v175, 0x4000, v179
	global_load_lds_dwordx4 v[184:185], off
	v_subrev_u32_e32 v250, s6, v184
	v_add_u32_e32 v184, 0x10040, v174
	v_ashrrev_i32_e32 v185, 31, v184
	v_lshlrev_b64 v[184:185], 1, v[184:185]
	v_readfirstlane_b32 s20, v175
	v_lshl_add_u64 v[182:183], s[6:7], 0, v[184:185]
	s_mov_b32 m0, s20
	v_add_u32_e32 v217, 0x6000, v179
	global_load_lds_dwordx4 v[182:183], off
	v_subrev_u32_e32 v249, s6, v182
	v_add_u32_e32 v182, 0x18040, v174
	v_ashrrev_i32_e32 v183, 31, v182
	v_lshlrev_b64 v[182:183], 1, v[182:183]
	v_readfirstlane_b32 s20, v217
	v_lshl_add_u64 v[174:175], s[6:7], 0, v[182:183]
	s_mov_b32 m0, s20
	v_lshl_add_u64 v[176:177], s[8:9], 0, v[176:177]
	global_load_lds_dwordx4 v[174:175], off
	v_subrev_u32_e32 v248, s6, v174
	v_add_u32_e32 v174, 0x8000, v179
	s_nop 0
	v_readfirstlane_b32 s20, v174
	s_mov_b32 m0, s20
	s_nop 0
	global_load_lds_dwordx4 v[176:177], off
	v_subrev_u32_e32 v247, s8, v176
	v_lshl_add_u64 v[176:177], s[8:9], 0, v[180:181]
	v_add_u32_e32 v180, 0xa000, v179
	s_nop 0
	v_readfirstlane_b32 s20, v180
	v_add_u32_e32 v180, 0xc000, v179
	s_mov_b32 m0, s20
	v_readfirstlane_b32 s20, v180
	v_add_u32_e32 v179, 0xe000, v179
	global_load_lds_dwordx4 v[176:177], off
	v_subrev_u32_e32 v246, s8, v176
	v_lshl_add_u64 v[176:177], s[8:9], 0, v[184:185]
	s_mov_b32 m0, s20
	v_readfirstlane_b32 s20, v179
	global_load_lds_dwordx4 v[176:177], off
	v_subrev_u32_e32 v245, s8, v176
	v_lshl_add_u64 v[176:177], s[8:9], 0, v[182:183]
	s_mov_b32 m0, s20
	s_nop 0
	global_load_lds_dwordx4 v[176:177], off
	v_subrev_u32_e32 v244, s8, v176
	s_add_u32 s98, s6, 0x80
	s_addc_u32 s99, s7, 0
	s_add_u32 s100, s8, 0x80
	s_addc_u32 s101, s9, 0
	v_add_u32_e32 v137, s19, v132
	v_add_u32_e32 v178, v137, v131
	ds_read_b128 v[138:141], v178 offset:32768
	ds_read_b128 v[142:145], v178 offset:34816
	ds_read_b128 v[146:149], v178 offset:36864
	ds_read_b128 v[150:153], v178 offset:38912
	v_add_u32_e32 v137, v137, v130
	ds_read_b128 v[154:157], v137
	ds_read_b128 v[158:161], v137 offset:2048
	ds_read_b128 v[162:165], v137 offset:4096
	ds_read_b128 v[166:169], v137 offset:6144
	ds_read_b128 v[170:173], v137 offset:8192
	s_branch .Lg_rot819_main
.Lg_rot819_last:
	v_add_u32_e32 v137, s19, v132
	v_add_u32_e32 v178, v137, v131
	ds_read_b128 v[138:141], v178 offset:32768
	ds_read_b128 v[142:145], v178 offset:34816
	ds_read_b128 v[146:149], v178 offset:36864
	ds_read_b128 v[150:153], v178 offset:38912
	v_add_u32_e32 v137, v137, v130
	ds_read_b128 v[154:157], v137
	ds_read_b128 v[158:161], v137 offset:2048
	ds_read_b128 v[162:165], v137 offset:4096
	ds_read_b128 v[166:169], v137 offset:6144
	ds_read_b128 v[170:173], v137 offset:8192
	v_mfma_f32_16x16x32_bf16 v[60:63], v[186:189], v[190:193], v[60:63]
	v_mfma_f32_16x16x32_bf16 v[56:59], v[194:197], v[190:193], v[56:59]
	v_mfma_f32_16x16x32_bf16 v[52:55], v[198:201], v[190:193], v[52:55]
	v_mfma_f32_16x16x32_bf16 v[48:51], v[218:221], v[190:193], v[48:51]
	v_mfma_f32_16x16x32_bf16 v[44:47], v[186:189], v[222:225], v[44:47]
	v_mfma_f32_16x16x32_bf16 v[40:43], v[194:197], v[222:225], v[40:43]
	v_mfma_f32_16x16x32_bf16 v[36:39], v[198:201], v[222:225], v[36:39]
	v_mfma_f32_16x16x32_bf16 v[32:35], v[218:221], v[222:225], v[32:35]
	v_mfma_f32_16x16x32_bf16 v[28:31], v[186:189], v[226:229], v[28:31]
	v_mfma_f32_16x16x32_bf16 v[24:27], v[194:197], v[226:229], v[24:27]
	v_mfma_f32_16x16x32_bf16 v[20:23], v[198:201], v[226:229], v[20:23]
	v_mfma_f32_16x16x32_bf16 v[16:19], v[218:221], v[226:229], v[16:19]
	v_mfma_f32_16x16x32_bf16 v[8:11], v[186:189], v[230:233], v[8:11]
	v_mfma_f32_16x16x32_bf16 v[4:7], v[194:197], v[230:233], v[4:7]
	v_mfma_f32_16x16x32_bf16 v[0:3], v[198:201], v[230:233], v[0:3]
	v_mfma_f32_16x16x32_bf16 v[12:15], v[218:221], v[230:233], v[12:15]
